# wave reductions in ph_post and rmsnorm_b16 via DPP row ops plus readlane instead of six ds_bpermute round trips
# baseline (speedup 1.0000x reference)
; __device__ __forceinline__ unsigned cvt_pk_bf16(float lo, float hi) { unsigned r; asm volatile("v_cvt_pk_bf16_f32 %0, %1, %2" : "=v"(r) : "v"(lo), "v"(hi)); return r; }
; __device__ __forceinline__ int otid() { int t = threadIdx.x; asm volatile("" : "+v"(t)); return t; }
; __device__ __forceinline__ uint4 ntld_u4(const void* p) { const ntu4_t v = __builtin_nontemporal_load((const ntu4_t*)p); return make_uint4(v.x, v.y, v.z, v.w); }
; __device__ void ph_rmsnorm_rows_b16(const bf16_t* __restrict__ hb, const float* __restrict__ g, bf16_t* __restrict__ out) {
;     const int tid = otid(); const int lane = tid & 63, wid = tid >> 6;
;     for (int row = blockIdx.x * 8 + wid; row < T_TOK; row += gridDim.x * 8) {
;         const size_t ro = (size_t)row * DM; uint4 w[2]; float v[2][8]; float ss = 0.f;
; #pragma unroll
;         for (int i = 0; i < 2; ++i) w[i] = ntld_u4(hb + ro + (lane + 64 * i) * 8);
; #pragma unroll
;         for (int i = 0; i < 2; ++i) { const unsigned ww[4] = {w[i].x, w[i].y, w[i].z, w[i].w};
; #pragma unroll
;             for (int k = 0; k < 4; ++k) { v[i][2 * k] = __uint_as_float(ww[k] << 16); v[i][2 * k + 1] = __uint_as_float(ww[k] & 0xffff0000u); ss += v[i][2 * k] * v[i][2 * k] + v[i][2 * k + 1] * v[i][2 * k + 1]; } }
;         ss = wave_sum(ss);
;         const float r = rsqrtf(ss * (1.0f / DM) + RMS_EPS);
;         float4 gaa[2], gbb[2];
; #pragma unroll
;         for (int i = 0; i < 2; ++i) { const int e0 = (lane + 64 * i) * 8; gaa[i] = *(const float4*)(g + e0); gbb[i] = *(const float4*)(g + e0 + 4); }
; #pragma unroll
;         for (int i = 0; i < 2; ++i) { const int e0 = (lane + 64 * i) * 8; const float4 ga = gaa[i], gb = gbb[i];
;             uint4 o; o.x = pg8::cvt_pk_bf16(v[i][0] * r * ga.x, v[i][1] * r * ga.y); o.y = pg8::cvt_pk_bf16(v[i][2] * r * ga.z, v[i][3] * r * ga.w);
;             o.z = pg8::cvt_pk_bf16(v[i][4] * r * gb.x, v[i][5] * r * gb.y); o.w = pg8::cvt_pk_bf16(v[i][6] * r * gb.z, v[i][7] * r * gb.w);
;             *(uint4*)(out + ro + e0) = o; }
;     }
; }
.LBB0_15:
	v_ashrrev_i32_e32 v1, 31, v0
	v_lshlrev_b64 v[32:33], 11, v[0:1]
	v_lshl_add_u64 v[12:13], v[4:5], 0, v[32:33]
	global_load_dwordx4 v[8:11], v[12:13], off nt
	s_nop 0
	global_load_dwordx4 v[12:15], v[12:13], off offset:1024 nt
	v_mov_b32_e32 v1, v239
	v_lshlrev_b32_e32 v1, 2, v1
	v_xor_b32_e32 v38, 0x80, v1
	v_add_u32_e32 v0, s6, v0
	v_cmp_lt_i32_e64 s[38:39], s33, v0
	v_lshl_add_u64 v[32:33], v[6:7], 0, v[32:33]
	s_or_b64 s[10:11], s[38:39], s[10:11]
	s_waitcnt vmcnt(1)
	v_and_b32_e32 v40, 0xffff0000, v8
	v_and_b32_e32 v42, 0xffff0000, v9
	v_lshlrev_b32_e32 v39, 16, v8
	v_lshlrev_b32_e32 v41, 16, v9
	v_and_b32_e32 v44, 0xffff0000, v10
	v_mul_f32_e32 v47, v40, v40
	v_mul_f32_e32 v48, v42, v42
	v_lshlrev_b32_e32 v43, 16, v10
	v_and_b32_e32 v46, 0xffff0000, v11
	v_mul_f32_e32 v49, v44, v44
	v_fmac_f32_e32 v47, v39, v39
	v_fmac_f32_e32 v48, v41, v41
	v_lshlrev_b32_e32 v45, 16, v11
	s_waitcnt vmcnt(0)
	v_and_b32_e32 v11, 0xffff0000, v13
	v_and_b32_e32 v10, 0xffff0000, v12
	v_mul_f32_e32 v50, v46, v46
	v_fmac_f32_e32 v49, v43, v43
	v_add_f32_e32 v47, v47, v48
	v_lshlrev_b32_e32 v9, 16, v13
	v_lshlrev_b32_e32 v8, 16, v12
	v_pk_mul_f32 v[34:35], v[10:11], v[10:11]
	v_fmac_f32_e32 v50, v45, v45
	v_add_f32_e32 v47, v49, v47
	v_lshlrev_b32_e32 v13, 16, v15
	v_lshlrev_b32_e32 v12, 16, v14
	v_and_b32_e32 v15, 0xffff0000, v15
	v_and_b32_e32 v14, 0xffff0000, v14
	v_pk_fma_f32 v[34:35], v[8:9], v[8:9], v[34:35]
	v_add_f32_e32 v47, v50, v47
	v_pk_mul_f32 v[36:37], v[14:15], v[14:15]
	v_add_f32_e32 v34, v34, v47
	v_pk_fma_f32 v[36:37], v[12:13], v[12:13], v[36:37]
	v_add_f32_e32 v34, v35, v34
	v_add_f32_e32 v34, v36, v34
	v_add_f32_e32 v34, v37, v34
	s_nop 1
	v_add_f32_dpp v35, v34, v34 quad_perm:[1,0,3,2] row_mask:0xf bank_mask:0xf
	s_nop 1
	v_add_f32_dpp v34, v35, v35 quad_perm:[2,3,0,1] row_mask:0xf bank_mask:0xf
	s_nop 1
	v_add_f32_dpp v35, v34, v34 row_half_mirror row_mask:0xf bank_mask:0xf
	s_nop 1
	v_add_f32_dpp v34, v35, v35 row_mirror row_mask:0xf bank_mask:0xf
	s_nop 1
	v_readlane_b32 s0, v34, 0
	v_readlane_b32 s1, v34, 16
	v_readlane_b32 s18, v34, 32
	v_readlane_b32 s19, v34, 48
	v_mov_b32_e32 v1, s0
	v_add_f32_e32 v1, s1, v1
	v_add_f32_e32 v1, s18, v1
	v_add_f32_e32 v1, s19, v1
	v_fmamk_f32 v1, v1, 0x3a800000, v194
	v_mul_f32_e32 v34, 0x4b800000, v1
	v_cmp_gt_f32_e32 vcc, s23, v1
	s_nop 1
	v_cndmask_b32_e32 v1, v1, v34, vcc
	v_rsq_f32_e32 v1, v1
	s_nop 0
	v_mul_f32_e32 v34, 0x45800000, v1
	v_cndmask_b32_e32 v1, v1, v34, vcc
	v_mul_f32_e32 v34, v1, v39
	v_mul_f32_e32 v35, v1, v40
	v_mul_f32_e32 v36, v1, v41
	v_mul_f32_e32 v37, v1, v42
	v_mul_f32_e32 v38, v1, v43
	v_mul_f32_e32 v39, v1, v44
	v_mul_f32_e32 v40, v1, v45
	v_mul_f32_e32 v41, v1, v46
	v_mul_f32_e32 v8, v1, v8
	v_mul_f32_e32 v10, v1, v10
	v_mul_f32_e32 v9, v1, v9
	v_mul_f32_e32 v11, v1, v11
	v_mul_f32_e32 v12, v1, v12
	v_mul_f32_e32 v14, v1, v14
	v_mul_f32_e32 v13, v1, v13
	v_mul_f32_e32 v1, v1, v15
	v_mul_f32_e32 v15, v108, v34
	v_mul_f32_e32 v20, v109, v35
	v_mul_f32_e32 v21, v110, v36
	v_mul_f32_e32 v22, v111, v37
	v_mul_f32_e32 v16, v104, v38
	v_mul_f32_e32 v17, v105, v39
	v_mul_f32_e32 v18, v106, v40
	v_mul_f32_e32 v19, v107, v41
	v_mul_f32_e32 v23, v116, v8
	v_mul_f32_e32 v28, v117, v10
	v_mul_f32_e32 v29, v118, v9
	v_mul_f32_e32 v30, v119, v11
	v_cvt_pk_bf16_f32 v8, v15, v20
	v_cvt_pk_bf16_f32 v9, v21, v22
	v_cvt_pk_bf16_f32 v10, v16, v17
	v_cvt_pk_bf16_f32 v11, v18, v19
	v_mul_f32_e32 v12, v112, v12
	v_mul_f32_e32 v14, v113, v14
	v_mul_f32_e32 v13, v114, v13
	v_mul_f32_e32 v1, v115, v1
	global_store_dwordx4 v[32:33], v[8:11], off
	s_nop 1
	v_cvt_pk_bf16_f32 v8, v23, v28
	v_cvt_pk_bf16_f32 v9, v29, v30
	v_cvt_pk_bf16_f32 v10, v12, v14
	v_cvt_pk_bf16_f32 v11, v13, v1
	global_store_dwordx4 v[32:33], v[8:11], off offset:1024
	s_andn2_b64 exec, exec, s[10:11]
	s_cbranch_execnz .LBB0_15

; __device__ __forceinline__ uint4 ntld_u4(const void* p) { const ntu4_t v = __builtin_nontemporal_load((const ntu4_t*)p); return make_uint4(v.x, v.y, v.z, v.w); }
; __device__ __forceinline__ float4 ntld_f4(const void* p) { const ntf4_t v = __builtin_nontemporal_load((const ntf4_t*)p); return make_float4(v.x, v.y, v.z, v.w); }
; __device__ void ph_post(const float* hin_f, const bf16_t* hin_b, const bf16_t* t1, const float* gpost, bf16_t* E, const float* gple, bf16_t* h1b) {
;     ...
;         for (int i = 0; i < 2; ++i) { const int e0 = (lane + 64 * i) * 8; tw[i] = ntld_u4(t1 + ro + e0); ew[i] = ntld_u4(E + ro + e0); }
;         if (hin_b) {
; #pragma unroll
;             for (int i = 0; i < 2; ++i) { const uint4 hw = ntld_u4(hin_b + ro + (lane + 64 * i) * 8); unpack8(hw, hv[i]); }
;         } else {
; #pragma unroll
;             for (int i = 0; i < 2; ++i) { const int e0 = (lane + 64 * i) * 8; const float4 a = ntld_f4(hin_f + ro + e0), b = ntld_f4(hin_f + ro + e0 + 4);
;                 hv[i][0] = a.x; hv[i][1] = a.y; hv[i][2] = a.z; hv[i][3] = a.w; hv[i][4] = b.x; hv[i][5] = b.y; hv[i][6] = b.z; hv[i][7] = b.w; } }
;         float tv[2][8], ev[2][8]; float ss = 0.f, se = 0.f;
; #pragma unroll
;         for (int i = 0; i < 2; ++i) { unpack8(tw[i], tv[i]); unpack8(ew[i], ev[i]);
; #pragma unroll
;             for (int k = 0; k < 8; ++k) { ss += tv[i][k] * tv[i][k]; se += ev[i][k] * ev[i][k]; } }
.LBB0_769:
	s_waitcnt vmcnt(3)
	v_and_b32_e32 v85, 0xffff0000, v28
	s_waitcnt vmcnt(1)
	v_and_b32_e32 v84, 0xffff0000, v24
	v_lshlrev_b32_e32 v87, 16, v28
	v_lshlrev_b32_e32 v86, 16, v24
	v_lshlrev_b32_e32 v82, 16, v25
	v_and_b32_e32 v80, 0xffff0000, v25
	v_pk_mul_f32 v[24:25], v[84:85], v[84:85]
	v_lshlrev_b32_e32 v83, 16, v29
	v_pk_fma_f32 v[24:25], v[86:87], v[86:87], v[24:25]
	v_and_b32_e32 v81, 0xffff0000, v29
	v_lshlrev_b32_e32 v71, 16, v20
	v_and_b32_e32 v69, 0xffff0000, v20
	v_lshlrev_b32_e32 v67, 16, v21
	v_and_b32_e32 v63, 0xffff0000, v21
	v_pk_fma_f32 v[20:21], v[82:83], v[82:83], v[24:25]
	v_lshlrev_b32_e32 v79, 16, v30
	v_lshlrev_b32_e32 v78, 16, v26
	v_pk_fma_f32 v[20:21], v[80:81], v[80:81], v[20:21]
	v_and_b32_e32 v77, 0xffff0000, v30
	v_and_b32_e32 v76, 0xffff0000, v26
	v_pk_fma_f32 v[20:21], v[78:79], v[78:79], v[20:21]
	v_lshlrev_b32_e32 v75, 16, v31
	v_lshlrev_b32_e32 v74, 16, v27
	v_and_b32_e32 v60, 0xffff0000, v22
	v_lshlrev_b32_e32 v61, 16, v22
	v_pk_fma_f32 v[20:21], v[76:77], v[76:77], v[20:21]
	v_and_b32_e32 v73, 0xffff0000, v31
	v_and_b32_e32 v72, 0xffff0000, v27
	s_waitcnt vmcnt(0)
; __device__ __forceinline__ unsigned cvt_pk_bf16(float lo, float hi) { unsigned r; asm volatile("v_cvt_pk_bf16_f32 %0, %1, %2" : "=v"(r) : "v"(lo), "v"(hi)); return r; }
; __device__ void ph_post(const float* hin_f, const bf16_t* hin_b, const bf16_t* t1, const float* gpost, bf16_t* E, const float* gple, bf16_t* h1b) {
;     ...
;         ss = wave_sum(ss); se = wave_sum(se);
;         const float r = rsqrtf(ss * (1.0f / DM) + RMS_EPS), re = rsqrtf(se * (1.0f / DM) + RMS_EPS);
;         float4 gaa[2], gbb[2], paa[2], pbb[2];
; #pragma unroll
;         for (int i = 0; i < 2; ++i) { const int e0 = (lane + 64 * i) * 8; gaa[i] = *(const float4*)(gpost + e0); gbb[i] = *(const float4*)(gpost + e0 + 4); paa[i] = *(const float4*)(gple + e0); pbb[i] = *(const float4*)(gple + e0 + 4); }
; #pragma unroll
;         for (int i = 0; i < 2; ++i) { const int e0 = (lane + 64 * i) * 8;
;             const float4 ga = gaa[i], gb = gbb[i], pa = paa[i], pb = pbb[i];
;             const float gg[8] = {ga.x, ga.y, ga.z, ga.w, gb.x, gb.y, gb.z, gb.w}, pp[8] = {pa.x, pa.y, pa.z, pa.w, pb.x, pb.y, pb.z, pb.w};
;             float o[8], x[8];
; #pragma unroll
;             for (int k = 0; k < 8; ++k) { o[k] = hv[i][k] + tv[i][k] * r * gg[k]; x[k] = ev[i][k] * re * pp[k]; }
;             uint4 w; w.x = pg8::cvt_pk_bf16(o[0], o[1]); w.y = pg8::cvt_pk_bf16(o[2], o[3]); w.z = pg8::cvt_pk_bf16(o[4], o[5]); w.w = pg8::cvt_pk_bf16(o[6], o[7]);
;             *(uint4*)(h1b + ro + e0) = w;
;             uint4 xx; xx.x = pg8::cvt_pk_bf16(x[0], x[1]); xx.y = pg8::cvt_pk_bf16(x[2], x[3]); xx.z = pg8::cvt_pk_bf16(x[4], x[5]); xx.w = pg8::cvt_pk_bf16(x[6], x[7]);
;             *(uint4*)(E + ro + e0) = xx; }
;     }
	v_lshlrev_b32_e32 v70, 16, v16
	v_and_b32_e32 v68, 0xffff0000, v16
	v_lshlrev_b32_e32 v66, 16, v17
	v_and_b32_e32 v62, 0xffff0000, v17
	v_pk_mul_f32 v[16:17], v[60:61], v[60:61]
	v_pk_fma_f32 v[20:21], v[74:75], v[74:75], v[20:21]
	v_and_b32_e32 v56, 0xffff0000, v23
	v_lshlrev_b32_e32 v57, 16, v23
	v_pk_fma_f32 v[20:21], v[72:73], v[72:73], v[20:21]
	v_mov_b32_e32 v23, v17
	v_mov_b32_e32 v17, v239
	v_pk_fma_f32 v[20:21], v[70:71], v[70:71], v[20:21]
	v_and_b32_e32 v64, 0xffff0000, v18
	v_lshlrev_b32_e32 v65, 16, v18
	v_pk_fma_f32 v[20:21], v[68:69], v[68:69], v[20:21]
	v_lshlrev_b32_e32 v17, 2, v17
	v_and_b32_e32 v58, 0xffff0000, v19
	v_lshlrev_b32_e32 v59, 16, v19
	v_pk_mul_f32 v[18:19], v[64:65], v[64:65]
	v_pk_fma_f32 v[20:21], v[66:67], v[66:67], v[20:21]
	v_xor_b32_e32 v26, 0x80, v17
	v_xor_b32_e32 v27, 64, v17
	v_xor_b32_e32 v28, 32, v17
	v_xor_b32_e32 v29, 16, v17
	v_xor_b32_e32 v30, 8, v17
	v_xor_b32_e32 v31, 4, v17
	v_mov_b32_e32 v17, v239
	v_pk_fma_f32 v[20:21], v[62:63], v[62:63], v[20:21]
	v_mov_b32_e32 v22, v19
	v_pk_add_f32 v[20:21], v[22:23], v[20:21]
	v_pk_mul_f32 v[22:23], v[56:57], v[56:57]
	v_pk_mul_f32 v[24:25], v[58:59], v[58:59]
	v_lshlrev_b32_e32 v17, 2, v17
	v_mov_b32_e32 v19, v16
	v_xor_b32_e32 v32, 0x80, v17
	v_xor_b32_e32 v33, 64, v17
	v_xor_b32_e32 v34, 32, v17
	v_xor_b32_e32 v35, 16, v17
	v_xor_b32_e32 v37, 8, v17
	v_xor_b32_e32 v88, 4, v17
	v_pk_add_f32 v[16:17], v[18:19], v[20:21]
	v_mov_b32_e32 v18, v25
	v_mov_b32_e32 v19, v23
	v_pk_add_f32 v[16:17], v[18:19], v[16:17]
	v_mov_b32_e32 v25, v22
	v_pk_add_f32 v[16:17], v[24:25], v[16:17]
	s_mov_b32 s0, 0x3a800000
	v_add_u32_e32 v36, s12, v36
	s_nop 0
	v_add_f32_dpp v18, v16, v16 quad_perm:[1,0,3,2] row_mask:0xf bank_mask:0xf
	v_add_f32_dpp v19, v17, v17 quad_perm:[1,0,3,2] row_mask:0xf bank_mask:0xf
	s_nop 1
	v_add_f32_dpp v16, v18, v18 quad_perm:[2,3,0,1] row_mask:0xf bank_mask:0xf
	v_add_f32_dpp v17, v19, v19 quad_perm:[2,3,0,1] row_mask:0xf bank_mask:0xf
	s_nop 1
	v_add_f32_dpp v18, v16, v16 row_half_mirror row_mask:0xf bank_mask:0xf
	v_add_f32_dpp v19, v17, v17 row_half_mirror row_mask:0xf bank_mask:0xf
	s_nop 1
	v_add_f32_dpp v16, v18, v18 row_mirror row_mask:0xf bank_mask:0xf
	v_add_f32_dpp v17, v19, v19 row_mirror row_mask:0xf bank_mask:0xf
	s_nop 1
	v_readlane_b32 s10, v16, 0
	v_readlane_b32 s11, v16, 16
	v_readlane_b32 s18, v16, 32
	v_readlane_b32 s19, v16, 48
	v_readlane_b32 s24, v17, 0
	v_readlane_b32 s25, v17, 16
	v_readlane_b32 s26, v17, 32
	v_readlane_b32 s32, v17, 48
	v_mov_b32_e32 v16, s10
	v_mov_b32_e32 v17, s24
	v_add_f32_e32 v16, s11, v16
	v_add_f32_e32 v17, s25, v17
	v_add_f32_e32 v16, s18, v16
	v_add_f32_e32 v17, s26, v17
	v_add_f32_e32 v16, s19, v16
	v_add_f32_e32 v17, s32, v17
	s_nop 0
	v_pk_fma_f32 v[16:17], v[16:17], s[0:1], v[194:195] op_sel_hi:[1,0,0]
	s_nop 0
	v_mul_f32_e32 v18, 0x4b800000, v17
	v_cmp_gt_f32_e64 s[38:39], s23, v17
	v_cmp_gt_f32_e32 vcc, s23, v16
	s_nop 0
	v_cndmask_b32_e64 v17, v17, v18, s[38:39]
	v_rsq_f32_e32 v37, v17
	v_mul_f32_e32 v17, 0x4b800000, v16
	v_cndmask_b32_e32 v16, v16, v17, vcc
	v_rsq_f32_e32 v101, v16
	v_mul_f32_e32 v100, 0x45800000, v37
	v_cndmask_b32_e64 v37, v37, v100, s[38:39]
	v_mul_f32_e32 v102, 0x45800000, v101
	v_cndmask_b32_e32 v100, v101, v102, vcc
	v_mul_f32_e32 v87, v37, v87
	v_cmp_lt_i32_e32 vcc, s33, v36
	s_or_b64 s[14:15], vcc, s[14:15]
	v_fmac_f32_e32 v8, v108, v87
	v_mul_f32_e32 v28, v100, v86
	v_mul_f32_e32 v28, v116, v28
	v_mul_f32_e32 v32, v37, v85
	v_fmac_f32_e32 v9, v109, v32
	v_mul_f32_e32 v32, v37, v83
	v_fmac_f32_e32 v10, v32, v110
	v_mul_f32_e32 v32, v37, v81
	v_fmac_f32_e32 v11, v32, v111
	v_mul_f32_e32 v32, v37, v79
	v_fmac_f32_e32 v12, v32, v104
	v_mul_f32_e32 v16, v100, v78
	v_mul_f32_e32 v16, v16, v112
	v_mul_f32_e32 v24, v37, v77
	v_fmac_f32_e32 v13, v24, v105
	v_mul_f32_e32 v24, v37, v75
	v_fmac_f32_e32 v14, v24, v106
	v_mul_f32_e32 v24, v37, v73
	v_mul_f32_e32 v29, v100, v84
	v_mul_f32_e32 v30, v100, v82
	v_mul_f32_e32 v31, v100, v80
	v_mul_f32_e32 v17, v100, v76
	v_mul_f32_e32 v18, v100, v74
	v_fmac_f32_e32 v15, v24, v107
	v_mul_f32_e32 v19, v100, v72
	v_cvt_pk_bf16_f32 v8, v8, v9
	v_cvt_pk_bf16_f32 v9, v10, v11
	v_cvt_pk_bf16_f32 v10, v12, v13
	v_cvt_pk_bf16_f32 v11, v14, v15
	v_lshl_add_u64 v[12:13], v[54:55], 1, v[50:51]
	v_mul_f32_e32 v29, v29, v117
	v_mul_f32_e32 v30, v30, v118
	v_mul_f32_e32 v31, v31, v119
	v_mul_f32_e32 v17, v17, v113
	v_mul_f32_e32 v18, v18, v114
	v_mul_f32_e32 v19, v19, v115
	global_store_dwordx4 v[12:13], v[8:11], off
	v_mul_f32_e32 v14, v37, v61
	v_mul_f32_e32 v15, v37, v60
	v_cvt_pk_bf16_f32 v8, v28, v29
	v_cvt_pk_bf16_f32 v9, v30, v31
	v_cvt_pk_bf16_f32 v10, v16, v17
	v_cvt_pk_bf16_f32 v11, v18, v19
	global_store_dwordx4 v[52:53], v[8:11], off
	v_mul_f32_e32 v16, v37, v57
	v_mul_f32_e32 v17, v37, v56
	v_mul_f32_e32 v8, v37, v71
	v_mul_f32_e32 v9, v37, v69
	v_mul_f32_e32 v10, v37, v67
	v_mul_f32_e32 v11, v37, v63
	v_fmac_f32_e32 v0, v8, v124
	v_fmac_f32_e32 v1, v9, v125
	v_fmac_f32_e32 v2, v10, v126
	v_fmac_f32_e32 v3, v11, v127
	v_mul_f32_e32 v8, v100, v70
	v_mul_f32_e32 v9, v100, v68
	v_mul_f32_e32 v10, v100, v66
	v_mul_f32_e32 v11, v100, v62
	v_fmac_f32_e32 v4, v14, v120
	v_mul_f32_e32 v14, v100, v65
	v_fmac_f32_e32 v5, v15, v121
	v_mul_f32_e32 v15, v100, v64
	v_fmac_f32_e32 v6, v16, v122
	v_mul_f32_e32 v16, v100, v59
	v_fmac_f32_e32 v7, v17, v123
	v_mul_f32_e32 v17, v100, v58
	v_cvt_pk_bf16_f32 v0, v0, v1
	v_cvt_pk_bf16_f32 v1, v2, v3
	v_cvt_pk_bf16_f32 v2, v4, v5
	v_cvt_pk_bf16_f32 v3, v6, v7
	v_mul_f32_e32 v8, v8, v132
	v_mul_f32_e32 v9, v9, v133
	v_mul_f32_e32 v10, v10, v134
	v_mul_f32_e32 v11, v11, v135
	v_mul_f32_e32 v14, v14, v128
	v_mul_f32_e32 v15, v15, v129
	v_mul_f32_e32 v16, v16, v130
	v_mul_f32_e32 v17, v17, v131
	global_store_dwordx4 v[12:13], v[0:3], off offset:1024
	s_nop 1
	v_cvt_pk_bf16_f32 v0, v8, v9
	v_cvt_pk_bf16_f32 v1, v10, v11
	v_cvt_pk_bf16_f32 v2, v14, v15
	v_cvt_pk_bf16_f32 v3, v16, v17
	global_store_dwordx4 v[52:53], v[0:3], off offset:1024
	s_andn2_b64 exec, exec, s[14:15]
	s_cbranch_execz .LBB0_773
